# phase 0 converts only layer 0 and memory KV weights; next-layer transposes split 91 percent to scan CU-mates (136 tiles each) and 9 percent to attention workgroups after their queues drain
# speedup vs baseline: 1.0069x; 1.0069x over previous
; __device__ __forceinline__ void phase_w(const Params p, char* smem) {
;     ...
;   for (int t = lbid(); t < L_ * PER_L; t += gridDim.x) {
;     int l = t / PER_L, r = t % PER_L;
;     if (r < 7392) {
;       transpose_tile<true>((const float*)p.in[I_WIN] + (size_t)l * D_ * NIN, NIN, (u16*)(ws + OFF_WIN) + (size_t)l * NINP * D_, D_,
;                      r / 231, r % 231, tile);
.LBB0_149:
	s_lshr_b32 s0, s73, 6
	s_cmp_eq_u32 s0, 4
	s_cbranch_scc0 .Lnot_mate
	v_readlane_b32 s0, v244, 43
	s_cmp_gt_u32 s0, 2
	s_cbranch_scc1 .LBB0_248
	s_add_i32 s0, s0, 1
	s_mul_i32 s20, s0, 0x2768
	s_add_i32 s101, s20, 8703
	s_add_i32 s20, s20, s73
	s_sub_i32 s20, s20, 0x100
	s_mov_b32 s100, 64
	s_branch .Ltramp_554

; __device__ __forceinline__ void phase_w(const Params p, char* smem) {
;     ...
;   for (int t = lbid(); t < L_ * PER_L; t += gridDim.x) {
;     int l = t / PER_L, r = t % PER_L;
.Lattn_w:
	s_add_i32 s0, s0, 1
	s_mul_i32 s1, s0, 0x2768
	s_add_i32 s101, s1, 9575
	s_add_i32 s20, s20, s1
	s_add_i32 s20, s20, 8704
	s_movk_i32 s100, 0x180
	s_waitcnt lgkmcnt(0)
	s_barrier
	s_branch .Ltramp_554
